# prologue weight-transpose items: the 8 per-row norm-gain loads issued together before the first wait instead of 8 serial round trips
# speedup vs baseline: 1.0115x; 1.0115x over previous
.LBB0_786:
	s_lshl_b32 s14, s38, 6
	s_lshl_b64 vcc, s[12:13], 2
	v_or_b32_e32 v36, s14, v32
	s_add_u32 s40, s40, vcc_lo
	s_addc_u32 s41, s41, vcc_hi
	v_ashrrev_i32_e32 v37, 31, v36
	v_lshl_add_u64 v[4:5], s[40:41], 0, v[140:141]
	v_mul_lo_u32 v10, s16, v37
	v_mul_lo_u32 v8, s17, v36
	v_mad_u64_u32 v[6:7], s[40:41], s16, v36, 0
	v_add3_u32 v7, v7, v10, v8
	v_or_b32_e32 v8, 8, v36
	v_mul_lo_u32 v11, s17, v8
	v_mad_u64_u32 v[8:9], s[40:41], s16, v8, 0
	v_lshl_add_u64 v[6:7], v[6:7], 2, v[4:5]
	v_add3_u32 v9, v9, v10, v11
	v_lshl_add_u64 v[8:9], v[8:9], 2, v[4:5]
	global_load_dwordx4 v[48:51], v[6:7], off
	global_load_dwordx4 v[28:31], v[8:9], off
	v_or_b32_e32 v6, 16, v36
	v_mul_lo_u32 v8, s17, v6
	v_mad_u64_u32 v[6:7], s[40:41], s16, v6, 0
	v_add3_u32 v7, v7, v10, v8
	v_or_b32_e32 v8, 24, v36
	v_mul_lo_u32 v11, s17, v8
	v_mad_u64_u32 v[8:9], s[40:41], s16, v8, 0
	v_lshl_add_u64 v[6:7], v[6:7], 2, v[4:5]
	v_add3_u32 v9, v9, v10, v11
	v_lshl_add_u64 v[8:9], v[8:9], 2, v[4:5]
	global_load_dwordx4 v[24:27], v[6:7], off
	global_load_dwordx4 v[20:23], v[8:9], off
	v_or_b32_e32 v6, 32, v36
	v_mul_lo_u32 v8, s17, v6
	v_mad_u64_u32 v[6:7], s[40:41], s16, v6, 0
	v_add3_u32 v7, v7, v10, v8
	v_or_b32_e32 v8, 40, v36
	v_mul_lo_u32 v11, s17, v8
	v_mad_u64_u32 v[8:9], s[40:41], s16, v8, 0
	v_lshl_add_u64 v[6:7], v[6:7], 2, v[4:5]
	v_add3_u32 v9, v9, v10, v11
	v_lshl_add_u64 v[8:9], v[8:9], 2, v[4:5]
	global_load_dwordx4 v[16:19], v[6:7], off
	global_load_dwordx4 v[12:15], v[8:9], off
	v_or_b32_e32 v6, 48, v36
	v_mul_lo_u32 v8, s17, v6
	v_mad_u64_u32 v[6:7], s[40:41], s16, v6, 0
	v_add3_u32 v7, v7, v10, v8
	v_or_b32_e32 v8, 56, v36
	v_mul_lo_u32 v11, s17, v8
	v_mad_u64_u32 v[8:9], s[16:17], s16, v8, 0
	v_add3_u32 v9, v9, v10, v11
	v_lshl_add_u64 v[6:7], v[6:7], 2, v[4:5]
	v_lshl_add_u64 v[4:5], v[8:9], 2, v[4:5]
	global_load_dwordx4 v[8:11], v[6:7], off
	s_nop 0
	global_load_dwordx4 v[4:7], v[4:5], off
	s_cmp_eq_u64 s[10:11], 0
	s_cbranch_scc1 .Lks_skip
	v_lshl_add_u64 v[60:61], v[36:37], 2, s[10:11]
	global_load_dword v62, v[60:61], off
	global_load_dword v64, v[60:61], off offset:32
	global_load_dword v66, v[60:61], off offset:64
	global_load_dword v68, v[60:61], off offset:96
	global_load_dword v70, v[60:61], off offset:128
	global_load_dword v72, v[60:61], off offset:160
	global_load_dword v74, v[60:61], off offset:192
	global_load_dword v76, v[60:61], off offset:224
.Lks_skip:
	s_cmp_lg_u64 s[10:11], 0
	s_cselect_b64 s[16:17], -1, 0
	s_cmp_eq_u64 s[10:11], 0
	s_waitcnt vmcnt(0)
	v_pk_mul_f32 v[38:39], v[2:3], v[50:51]
	v_pk_mul_f32 v[40:41], v[0:1], v[48:49]
	s_cbranch_scc1 .LBB0_788
	v_lshl_add_u64 v[36:37], v[36:37], 2, s[10:11]
	v_mov_b32_e32 v36, v62
	s_nop 0
	v_pk_mul_f32 v[38:39], v[38:39], v[36:37] op_sel_hi:[1,0]
	v_pk_mul_f32 v[40:41], v[40:41], v[36:37] op_sel_hi:[1,0]
.LBB0_788:
	v_cndmask_b32_e64 v35, 0, 1, s[16:17]
	v_pk_mul_f32 v[30:31], v[2:3], v[30:31]
	v_cmp_ne_u32_e64 s[40:41], 1, v35
	s_andn2_b64 vcc, exec, s[16:17]
	v_pk_mul_f32 v[28:29], v[0:1], v[28:29]
	ds_write2_b32 v47, v40, v41 offset1:1
	ds_write2_b32 v47, v38, v39 offset0:2 offset1:3
	s_cbranch_vccnz .LBB0_790
	s_ashr_i32 s15, s14, 31
	v_lshl_add_u64 v[36:37], s[14:15], 0, v[32:33]
	v_lshl_add_u64 v[36:37], v[36:37], 2, s[10:11]
	v_mov_b32_e32 v36, v64
	s_nop 0
	v_pk_mul_f32 v[30:31], v[30:31], v[36:37] op_sel_hi:[1,0]
	v_pk_mul_f32 v[28:29], v[28:29], v[36:37] op_sel_hi:[1,0]
.LBB0_790:
	v_add_u32_e32 v35, 0x420, v47
	ds_write2_b32 v35, v28, v29 offset1:1
	v_add_u32_e32 v28, 0x428, v47
	v_pk_mul_f32 v[26:27], v[2:3], v[26:27]
	s_and_b64 vcc, exec, s[40:41]
	v_pk_mul_f32 v[24:25], v[0:1], v[24:25]
	ds_write2_b32 v28, v30, v31 offset1:1
	s_cbranch_vccnz .LBB0_792
	s_ashr_i32 s15, s14, 31
	v_lshl_add_u64 v[28:29], s[14:15], 0, v[32:33]
	v_lshl_add_u64 v[28:29], v[28:29], 2, s[10:11]
	v_mov_b32_e32 v28, v66
	s_nop 0
	v_pk_mul_f32 v[26:27], v[26:27], v[28:29] op_sel_hi:[1,0]
	v_pk_mul_f32 v[24:25], v[24:25], v[28:29] op_sel_hi:[1,0]
.LBB0_792:
	v_add_u32_e32 v28, 0x840, v47
	ds_write2_b32 v28, v24, v25 offset1:1
	v_add_u32_e32 v24, 0x848, v47
	v_pk_mul_f32 v[22:23], v[2:3], v[22:23]
	s_and_b64 vcc, exec, s[40:41]
	v_pk_mul_f32 v[20:21], v[0:1], v[20:21]
	ds_write2_b32 v24, v26, v27 offset1:1
	s_cbranch_vccnz .LBB0_794
	s_ashr_i32 s15, s14, 31
	v_lshl_add_u64 v[24:25], s[14:15], 0, v[32:33]
	v_lshl_add_u64 v[24:25], v[24:25], 2, s[10:11]
	v_mov_b32_e32 v24, v68
	s_nop 0
	v_pk_mul_f32 v[22:23], v[22:23], v[24:25] op_sel_hi:[1,0]
	v_pk_mul_f32 v[20:21], v[20:21], v[24:25] op_sel_hi:[1,0]
.LBB0_794:
	v_add_u32_e32 v24, 0xc60, v47
	ds_write2_b32 v24, v20, v21 offset1:1
	v_add_u32_e32 v20, 0xc68, v47
	v_pk_mul_f32 v[18:19], v[2:3], v[18:19]
	s_and_b64 vcc, exec, s[40:41]
	v_pk_mul_f32 v[16:17], v[0:1], v[16:17]
	ds_write2_b32 v20, v22, v23 offset1:1
	s_cbranch_vccnz .LBB0_796
	s_ashr_i32 s15, s14, 31
	v_lshl_add_u64 v[20:21], s[14:15], 0, v[32:33]
	v_lshl_add_u64 v[20:21], v[20:21], 2, s[10:11]
	v_mov_b32_e32 v20, v70
	s_nop 0
	v_pk_mul_f32 v[18:19], v[18:19], v[20:21] op_sel_hi:[1,0]
	v_pk_mul_f32 v[16:17], v[16:17], v[20:21] op_sel_hi:[1,0]
.LBB0_796:
	v_add_u32_e32 v20, 0x1080, v47
	ds_write2_b32 v20, v16, v17 offset1:1
	v_add_u32_e32 v16, 0x1088, v47
	v_pk_mul_f32 v[14:15], v[2:3], v[14:15]
	s_and_b64 vcc, exec, s[40:41]
	v_pk_mul_f32 v[12:13], v[0:1], v[12:13]
	ds_write2_b32 v16, v18, v19 offset1:1
	s_cbranch_vccnz .LBB0_798
	s_ashr_i32 s15, s14, 31
	v_lshl_add_u64 v[16:17], s[14:15], 0, v[32:33]
	v_lshl_add_u64 v[16:17], v[16:17], 2, s[10:11]
	v_mov_b32_e32 v16, v72
	s_nop 0
	v_pk_mul_f32 v[14:15], v[14:15], v[16:17] op_sel_hi:[1,0]
	v_pk_mul_f32 v[12:13], v[12:13], v[16:17] op_sel_hi:[1,0]
.LBB0_798:
	v_add_u32_e32 v16, 0x14a0, v47
	ds_write2_b32 v16, v12, v13 offset1:1
	v_add_u32_e32 v12, 0x14a8, v47
	v_pk_mul_f32 v[10:11], v[2:3], v[10:11]
	s_and_b64 vcc, exec, s[40:41]
	v_pk_mul_f32 v[8:9], v[0:1], v[8:9]
	ds_write2_b32 v12, v14, v15 offset1:1
	s_cbranch_vccnz .LBB0_800
	s_ashr_i32 s15, s14, 31
	v_lshl_add_u64 v[12:13], s[14:15], 0, v[32:33]
	v_lshl_add_u64 v[12:13], v[12:13], 2, s[10:11]
	v_mov_b32_e32 v12, v74
	s_nop 0
	v_pk_mul_f32 v[10:11], v[10:11], v[12:13] op_sel_hi:[1,0]
	v_pk_mul_f32 v[8:9], v[8:9], v[12:13] op_sel_hi:[1,0]
.LBB0_800:
	v_add_u32_e32 v12, 0x18c0, v47
	ds_write2_b32 v12, v8, v9 offset1:1
	v_add_u32_e32 v8, 0x18c8, v47
	v_pk_mul_f32 v[2:3], v[2:3], v[6:7]
	v_pk_mul_f32 v[0:1], v[0:1], v[4:5]
	s_and_b64 vcc, exec, s[16:17]
	ds_write2_b32 v8, v10, v11 offset1:1
	s_cbranch_vccz .LBB0_802
	s_ashr_i32 s15, s14, 31
	v_lshl_add_u64 v[4:5], s[14:15], 0, v[32:33]
	v_lshl_add_u64 v[4:5], v[4:5], 2, s[10:11]
	v_mov_b32_e32 v4, v76
	s_nop 0
	v_pk_mul_f32 v[6:7], v[2:3], v[4:5] op_sel_hi:[1,0]
	v_pk_mul_f32 v[4:5], v[0:1], v[4:5] op_sel_hi:[1,0]
	s_cbranch_execnz .LBB0_726
	s_branch .LBB0_725
